# nt hint also on LN streaming row loads (ln_in_rows x, ln1/ln2 Zb) in addition to peer_out H/TV loads
# baseline (speedup 1.0000x reference)
; DI int otid() { int t = __builtin_amdgcn_workitem_id_x(); asm volatile("" : "+v"(t)); return t; }
; DI unsigned pack2(float a, float b) { const f32x2 v = {a, b}; return __builtin_bit_cast(unsigned, __builtin_convertvector(v, bf16v2)); }
; DI void ln_in_rows(const float* __restrict__ src, const float* __restrict__ g, const float* __restrict__ bta, const float* __restrict__ w_in, u16* __restrict__ dst, float* __restrict__ G, float* Wg) {
;   const int lane = otid() & 63, wave = otid() >> 6;
;   for (int e = otid(); e < 8192; e += 512) Wg[e] = w_in[(size_t)(e >> 3) * 3592 + 3584 + (e & 7)];
;   __syncthreads();
;   float4 nv[4];
;   { const int row = blockIdx.x * 8 + wave; for (int i = 0; i < 4; ++i) nv[i] = *(const float4*)(src + (size_t)row * 1024 + i * 256 + lane * 4); }
;   for (int row = blockIdx.x * 8 + wave; row < T_TOK; row += gridDim.x * 8) {
;     float4 v[4];
;     float s = 0.f;
;     for (int i = 0; i < 4; ++i) { v[i] = nv[i]; s += v[i].x + v[i].y + v[i].z + v[i].w; }
;     { const int nrow = row + gridDim.x * 8; if (nrow < T_TOK) for (int i = 0; i < 4; ++i) nv[i] = *(const float4*)(src + (size_t)nrow * 1024 + i * 256 + lane * 4); }
;     const float mu = wsum(s) * (1.f / 1024.f);
;     float q = 0.f;
;     for (int i = 0; i < 4; ++i) { float a = v[i].x - mu, b = v[i].y - mu, c = v[i].z - mu, d = v[i].w - mu; q += a * a + b * b + c * c + d * d; }
;     const float rstd = rsqrtf(wsum(q) * (1.f / 1024.f) + LN_EPS);
;     float pg[8];
; #pragma unroll
;     for (int j = 0; j < 8; ++j) pg[j] = 0.f;
; #pragma unroll
;     for (int i = 0; i < 4; ++i) {
;       const int c0 = i * 256 + lane * 4;
;       float4 gg = *(const float4*)(g + c0), bb = *(const float4*)(bta + c0);
;       float y[4];
;       y[0] = (v[i].x - mu) * rstd * gg.x + bb.x; y[1] = (v[i].y - mu) * rstd * gg.y + bb.y; y[2] = (v[i].z - mu) * rstd * gg.z + bb.z; y[3] = (v[i].w - mu) * rstd * gg.w + bb.w;
;       uint2 o; o.x = pack2(y[0], y[1]); o.y = pack2(y[2], y[3]);
;       *(uint2*)(dst + (size_t)row * 1024 + c0) = o;
; #pragma unroll
;       for (int e = 0; e < 4; ++e) {
;         const float4 w0 = *(const float4*)(Wg + (c0 + e) * 8), w1 = *(const float4*)(Wg + (c0 + e) * 8 + 4);
;         pg[0] += y[e] * w0.x; pg[1] += y[e] * w0.y; pg[2] += y[e] * w0.z; pg[3] += y[e] * w0.w;
;         pg[4] += y[e] * w1.x; pg[5] += y[e] * w1.y; pg[6] += y[e] * w1.z; pg[7] += y[e] * w1.w;
;       }
.LBB0_165:
	s_or_b64 exec, exec, s[0:1]
	s_add_u32 s0, s68, 0x6300000
	s_addc_u32 s1, s69, 0
	v_writelane_b32 v250, s0, 19
	v_ashrrev_i32_e32 v1, 6, v1
	s_mov_b32 s2, 0x10000
	v_writelane_b32 v250, s1, 20
	s_lshl_b32 s1, s94, 3
	s_lshl_b32 s0, s70, 3
	s_add_u32 s24, s68, 0x6800000
	v_add_u32_e32 v194, s1, v1
	v_writelane_b32 v250, s0, 23
	s_addc_u32 s25, s69, 0
	v_cmp_gt_i32_e32 vcc, s2, v194
	s_waitcnt lgkmcnt(0)
	s_barrier
	v_writelane_b32 v250, s1, 27
	s_and_saveexec_b64 s[4:5], vcc
	s_cbranch_execz .LBB0_172
	v_ashrrev_i32_e32 v195, 31, v194
	v_and_b32_e32 v162, 63, v90
	v_lshlrev_b64 v[2:3], 12, v[194:195]
	v_mbcnt_hi_u32_b32 v34, -1, v203
	v_lshl_add_u64 v[2:3], s[52:53], 0, v[2:3]
	v_lshlrev_b32_e32 v196, 4, v162
	v_mov_b32_e32 v197, 0
	v_and_b32_e32 v1, 64, v34
	v_lshl_add_u64 v[2:3], v[2:3], 0, v[196:197]
	v_add_u32_e32 v35, 64, v1
	v_xor_b32_e32 v1, 32, v34
	global_load_dwordx4 v[178:181], v[2:3], off offset:3072 nt
	global_load_dwordx4 v[182:185], v[2:3], off offset:2048 nt
	global_load_dwordx4 v[186:189], v[2:3], off offset:1024 nt
	global_load_dwordx4 v[190:193], v[2:3], off nt
	v_cmp_lt_i32_e32 vcc, v1, v35
	v_xor_b32_e32 v2, 16, v34
	v_xor_b32_e32 v36, 2, v34
	v_cndmask_b32_e32 v1, v34, v1, vcc
	v_cmp_lt_i32_e32 vcc, v2, v35
	v_readlane_b32 s0, v250, 19
	v_readlane_b32 s1, v250, 20
	v_cndmask_b32_e32 v2, v34, v2, vcc
	v_lshlrev_b32_e32 v205, 2, v2
	v_xor_b32_e32 v2, 8, v34
	v_cmp_lt_i32_e32 vcc, v2, v35
	v_and_b32_e32 v91, 32, v90
	v_lshrrev_b32_e32 v204, 3, v91
	v_cndmask_b32_e32 v2, v34, v2, vcc
	v_lshlrev_b32_e32 v207, 2, v2
	v_xor_b32_e32 v2, 4, v34
	v_cmp_lt_i32_e32 vcc, v2, v35
	v_lshl_add_u32 v158, v162, 7, 0
	v_lshl_add_u64 v[198:199], s[52:53], 0, v[196:197]
	v_cndmask_b32_e32 v2, v34, v2, vcc
	v_lshlrev_b32_e32 v209, 2, v2
	global_load_dwordx4 v[2:5], v196, s[56:57]
	global_load_dwordx4 v[6:9], v196, s[58:59]
	global_load_dwordx4 v[10:13], v196, s[56:57] offset:1024
	global_load_dwordx4 v[14:17], v196, s[58:59] offset:1024
	global_load_dwordx4 v[18:21], v196, s[56:57] offset:2048
	global_load_dwordx4 v[22:25], v196, s[58:59] offset:2048
	global_load_dwordx4 v[26:29], v196, s[56:57] offset:3072
	global_load_dwordx4 v[30:33], v196, s[58:59] offset:3072
	v_cmp_lt_i32_e32 vcc, v36, v35
	v_bfe_u32 v228, v90, 3, 1
	v_lshlrev_b32_e32 v162, 3, v162
	v_cndmask_b32_e32 v36, v34, v36, vcc
	v_lshlrev_b32_e32 v211, 2, v36
	v_xor_b32_e32 v36, 1, v34
	v_cmp_lt_i32_e32 vcc, v36, v35
	v_mov_b32_e32 v35, v197
	v_mov_b32_e32 v163, v197
	v_cndmask_b32_e32 v34, v34, v36, vcc
	v_lshlrev_b32_e32 v213, 2, v34
	v_and_b32_e32 v34, 7, v90
	v_cmp_eq_u32_e32 vcc, 0, v34
	v_bfe_u32 v34, v90, 1, 5
	v_lshl_add_u64 v[200:201], s[0:1], 0, v[34:35]
	v_cmp_eq_u32_e64 s[0:1], 0, v91
	v_and_b32_e32 v91, 16, v90
	v_lshrrev_b32_e32 v220, 3, v91
	v_cndmask_b32_e64 v202, 0, 4, s[0:1]
	v_cndmask_b32_e64 v206, 1, 5, s[0:1]
	v_cndmask_b32_e64 v208, 5, 1, s[0:1]
	v_cndmask_b32_e64 v210, 2, 6, s[0:1]
	v_cndmask_b32_e64 v212, 6, 2, s[0:1]
	v_cndmask_b32_e64 v214, 3, 7, s[0:1]
	v_cndmask_b32_e64 v216, 7, 3, s[0:1]
	v_cmp_eq_u32_e64 s[0:1], 0, v91
	v_lshrrev_b32_e32 v91, 3, v90
	ds_read_b128 v[34:37], v158
	ds_read_b128 v[38:41], v158 offset:16
	ds_read_b128 v[42:45], v158 offset:32
	ds_read_b128 v[46:49], v158 offset:48
	ds_read_b128 v[50:53], v158 offset:64
	ds_read_b128 v[54:57], v158 offset:80
	ds_read_b128 v[58:61], v158 offset:96
	ds_read_b128 v[62:65], v158 offset:112
	ds_read_b128 v[66:69], v158 offset:8192
	ds_read_b128 v[70:73], v158 offset:8208
	ds_read_b128 v[74:77], v158 offset:8224
	ds_read_b128 v[78:81], v158 offset:8240
	ds_read_b128 v[82:85], v158 offset:8256
	ds_read_b128 v[86:89], v158 offset:8272
	v_bitop3_b32 v196, v91, 1, v91 bitop3:0xc
	ds_read_b128 v[90:93], v158 offset:8288
	ds_read_b128 v[94:97], v158 offset:8304
	ds_read_b128 v[98:101], v158 offset:16384
	ds_read_b128 v[102:105], v158 offset:16400
	ds_read_b128 v[106:109], v158 offset:16416
	ds_read_b128 v[110:113], v158 offset:16432
	ds_read_b128 v[114:117], v158 offset:16448
	ds_read_b128 v[118:121], v158 offset:16464
	ds_read_b128 v[122:125], v158 offset:16480
	ds_read_b128 v[126:129], v158 offset:16496
	ds_read_b128 v[130:133], v158 offset:24576
	ds_read_b128 v[134:137], v158 offset:24592
	ds_read_b128 v[138:141], v158 offset:24608
	ds_read_b128 v[142:145], v158 offset:24624
	ds_read_b128 v[146:149], v158 offset:24640
	ds_read_b128 v[150:153], v158 offset:24656
	ds_read_b128 v[154:157], v158 offset:24672
	ds_read_b128 v[158:161], v158 offset:24688
	v_lshlrev_b32_e32 v1, 2, v1
	v_cndmask_b32_e64 v218, 0, 2, s[0:1]
	v_cndmask_b32_e64 v224, 1, 3, s[0:1]
	v_cndmask_b32_e64 v226, 3, 1, s[0:1]
	v_mov_b32_e32 v229, v197
	v_lshl_add_u64 v[230:231], s[24:25], 0, v[162:163]
	s_mov_b64 s[6:7], 0
	s_mov_b32 s3, 0xffff
	v_mov_b32_e32 v215, 0x3727c5ac
	s_mov_b32 s12, 0x800000
	s_waitcnt vmcnt(11)
	v_mov_b64_e32 v[174:175], v[178:179]
	s_waitcnt vmcnt(10)
	v_mov_b64_e32 v[170:171], v[182:183]
	s_waitcnt vmcnt(9)
	v_mov_b64_e32 v[166:167], v[186:187]
	s_waitcnt vmcnt(8)
	v_mov_b64_e32 v[162:163], v[190:191]
	v_mov_b64_e32 v[164:165], v[192:193]
	v_mov_b64_e32 v[168:169], v[188:189]
	v_mov_b64_e32 v[172:173], v[184:185]
	v_mov_b64_e32 v[176:177], v[180:181]
	s_branch .LBB0_168

; DI void ln_in_rows(const float* __restrict__ src, const float* __restrict__ g, const float* __restrict__ bta, const float* __restrict__ w_in, u16* __restrict__ dst, float* __restrict__ G, float* Wg) {
;     ...
;   for (int row = blockIdx.x * 8 + wave; row < T_TOK; row += gridDim.x * 8) {
;     float4 v[4];
;     float s = 0.f;
;     for (int i = 0; i < 4; ++i) { v[i] = nv[i]; s += v[i].x + v[i].y + v[i].z + v[i].w; }
;     { const int nrow = row + gridDim.x * 8; if (nrow < T_TOK) for (int i = 0; i < 4; ++i) nv[i] = *(const float4*)(src + (size_t)nrow * 1024 + i * 256 + lane * 4); }
.LBB0_168:
	v_readlane_b32 s0, v250, 23
	s_nop 1
	v_add_u32_e32 v232, s0, v194
	v_cmp_gt_i32_e64 s[8:9], s2, v232
	v_cmp_lt_i32_e64 s[0:1], s3, v232
	s_and_saveexec_b64 s[10:11], s[8:9]
	s_cbranch_execz .LBB0_170
	v_ashrrev_i32_e32 v233, 31, v232
	v_lshlrev_b64 v[162:163], 12, v[232:233]
	v_lshl_add_u64 v[174:175], v[198:199], 0, v[162:163]
	global_load_dwordx4 v[162:165], v[174:175], off nt
	global_load_dwordx4 v[166:169], v[174:175], off offset:1024 nt
	global_load_dwordx4 v[170:173], v[174:175], off offset:2048 nt
	s_nop 0
	global_load_dwordx4 v[174:177], v[174:175], off offset:3072 nt

; DI void ln_rows_b(const u16* __restrict__ Zb, const float* __restrict__ g, const float* __restrict__ bta, u16* __restrict__ H) {
;     ...
;   for (int row0 = blockIdx.x * 8 + wave; row0 < T_TOK; row0 += stride * 4) {
;     uint4 r[4][2];
; #pragma unroll
;     for (int j = 0; j < 4; ++j) {
;       const int row = row0 + j * stride;
;       if (row < T_TOK) { r[j][0] = *(const uint4*)(Zb + (size_t)row * 1024 + lane * 16); r[j][1] = *(const uint4*)(Zb + (size_t)row * 1024 + lane * 16 + 8); }
;     }
.LBB0_759:
	v_ashrrev_i32_e32 v71, 31, v70
	v_lshlrev_b64 v[74:75], 11, v[70:71]
	v_lshl_add_u64 v[60:61], v[64:65], 0, v[74:75]
	global_load_dwordx4 v[56:59], v[60:61], off offset:16 nt
	s_nop 0
	global_load_dwordx4 v[60:63], v[60:61], off nt
	v_add_u32_e32 v68, s60, v70
	v_cmp_gt_i32_e64 s[4:5], s2, v68
	v_ashrrev_i32_e32 v69, 31, v68
	s_and_saveexec_b64 s[0:1], s[4:5]
	s_cbranch_execz .LBB0_761
	v_lshlrev_b64 v[48:49], 11, v[68:69]
	v_lshl_add_u64 v[52:53], v[64:65], 0, v[48:49]
	global_load_dwordx4 v[48:51], v[52:53], off offset:16 nt
	s_nop 0
	global_load_dwordx4 v[52:55], v[52:53], off nt
.LBB0_761:
	s_or_b64 exec, exec, s[0:1]
	v_readlane_b32 s0, v250, 28
	s_nop 1
	v_add_u32_e32 v72, s0, v70
	v_cmp_gt_i32_e64 s[0:1], s2, v72
	v_ashrrev_i32_e32 v73, 31, v72
	s_and_saveexec_b64 s[8:9], s[0:1]
	s_cbranch_execz .LBB0_763
	v_lshlrev_b64 v[40:41], 11, v[72:73]
	v_lshl_add_u64 v[44:45], v[64:65], 0, v[40:41]
	global_load_dwordx4 v[40:43], v[44:45], off offset:16 nt
	s_nop 0
	global_load_dwordx4 v[44:47], v[44:45], off nt
.LBB0_763:
	s_or_b64 exec, exec, s[8:9]
	v_add_u32_e32 v70, s54, v70
	v_cmp_gt_i32_e32 vcc, s2, v70
	v_ashrrev_i32_e32 v71, 31, v70
	s_and_saveexec_b64 s[8:9], vcc
	s_cbranch_execz .LBB0_765
	v_lshlrev_b64 v[32:33], 11, v[70:71]
	v_lshl_add_u64 v[36:37], v[64:65], 0, v[32:33]
	global_load_dwordx4 v[32:35], v[36:37], off offset:16 nt
	s_nop 0
	global_load_dwordx4 v[36:39], v[36:37], off nt

; DI void ln_rows_b(const u16* __restrict__ Zb, const float* __restrict__ g, const float* __restrict__ bta, u16* __restrict__ H) {
;     ...
;   for (int row0 = blockIdx.x * 8 + wave; row0 < T_TOK; row0 += stride * 4) {
;     uint4 r[4][2];
; #pragma unroll
;     for (int j = 0; j < 4; ++j) {
;       const int row = row0 + j * stride;
;       if (row < T_TOK) { r[j][0] = *(const uint4*)(Zb + (size_t)row * 1024 + lane * 16); r[j][1] = *(const uint4*)(Zb + (size_t)row * 1024 + lane * 16 + 8); }
;     }
.LBB0_1043:
	v_ashrrev_i32_e32 v71, 31, v70
	v_lshlrev_b64 v[74:75], 11, v[70:71]
	v_lshl_add_u64 v[68:69], v[64:65], 0, v[74:75]
	global_load_dwordx4 v[56:59], v[68:69], off offset:16 nt
	global_load_dwordx4 v[60:63], v[68:69], off nt
	v_add_u32_e32 v68, s60, v70
	v_cmp_gt_i32_e64 s[4:5], s2, v68
	v_ashrrev_i32_e32 v69, 31, v68
	s_and_saveexec_b64 s[0:1], s[4:5]
	s_cbranch_execz .LBB0_1045
	v_lshlrev_b64 v[48:49], 11, v[68:69]
	v_lshl_add_u64 v[52:53], v[64:65], 0, v[48:49]
	global_load_dwordx4 v[48:51], v[52:53], off offset:16 nt
	s_nop 0
	global_load_dwordx4 v[52:55], v[52:53], off nt
